# HGRN c1: item staging loads batched (counted waits) and the dir-1 LB tile prefetched into registers after item staging (8 serialized round trips removed per item)
# speedup vs baseline: 1.0063x; 1.0004x over previous
; DEV int hg_row0(int cidx, int b) { return (cidx < 4) ? (MM + b * 256 + cidx * 64) : (b * 8192 + (cidx - 4) * 64); }
; DEV void phase_hg_c1(const Params& p, char* smem) {
;     ...
;     const int cidx = item >> 4, bh = item & 15, b = bh >> 3, h = bh & 7;
;     const int r0 = hg_row0(cidx, b);
;     __syncthreads();
; #pragma unroll
;     for (int i = 0; i < 4; i++) {
;       int id = tid + i * 256; int s = id >> 4, cc = id & 15;
;       uint4 u = *(const uint4*)(IH + (size_t)(r0 + s) * 1024 + h * 128 + cc * 8);
;       uint4 lf = *(const uint4*)(LFp + (size_t)(r0 + s) * 1024 + h * 128 + cc * 8);
;       *(uint4*)(RB + s * 144 + cc * 8) = lf;
;       bf16_t* vt = Vt + (cc * 8) * 80 + s;
;       vt[0] = (bf16_t)(u.x & 0xffff); vt[80] = (bf16_t)(u.x >> 16); vt[160] = (bf16_t)(u.y & 0xffff); vt[240] = (bf16_t)(u.y >> 16);
;       vt[320] = (bf16_t)(u.z & 0xffff); vt[400] = (bf16_t)(u.z >> 16); vt[480] = (bf16_t)(u.w & 0xffff); vt[560] = (bf16_t)(u.w >> 16);
;     }
; #pragma unroll 1
;     for (int dir = 0; dir < 2; dir++) {
;       bf16_t* stg = dir ? RA : RB;
;       bf16_t* kot = dir ? RB : RA;
;       if (dir == 1) {
;         __syncthreads();
; #pragma unroll
;         for (int i = 0; i < 4; i++) {
;           int id = tid + i * 256; int s = id >> 4, cc = id & 15;
;           *(uint4*)(RA + s * 144 + cc * 8) = *(const uint4*)(LBp + (size_t)(r0 + s) * 1024 + h * 128 + cc * 8);
;         }
.LBB0_305:
	s_ashr_i32 s11, s10, 4
	s_and_b32 s0, s10, 15
	s_bfe_u32 s1, s10, 0x10003
	s_lshl_b32 s2, s11, 6
	s_cmp_lt_i32 s11, 4
	s_movk_i32 s6, 0xff00
	s_cselect_b32 s3, 8, 13
	s_cselect_b32 s6, 0x4000, s6
	s_lshl_b32 s1, s1, s3
	s_add_i32 s2, s6, s2
	s_add_i32 s1, s2, s1
	s_lshl_b32 s2, s10, 8
	v_add_u32_e32 v22, s1, v36
	s_and_b32 s52, s2, 0x700
	v_ashrrev_i32_e32 v23, 31, v22
	v_lshl_add_u64 v[58:59], v[4:5], 0, s[52:53]
	v_lshl_add_u64 v[60:61], v[6:7], 0, s[52:53]
	v_bfe_u32 v160, v195, 2, 4
	v_lshrrev_b32_e32 v161, 6, v195
	v_and_b32_e32 v166, 3, v195
	v_lshl_or_b32 v161, v161, 2, v166
	v_lshrrev_b32_e32 v166, 4, v195
	v_sub_u32_e32 v160, v160, v166
	v_and_b32_e32 v166, 15, v195
	v_sub_u32_e32 v161, v161, v166
	v_lshlrev_b32_e32 v162, 11, v160
	v_lshl_add_u32 v162, v161, 4, v162
	v_ashrrev_i32_e32 v163, 31, v162
	v_mul_i32_i24_e32 v164, 0x500, v161
	v_lshl_add_u32 v164, v160, 1, v164
	v_lshlrev_b64 v[22:23], 11, v[22:23]
	v_add_u32_e32 v24, s1, v39
	v_ashrrev_i32_e32 v25, 31, v24
	v_lshlrev_b64 v[24:25], 11, v[24:25]
	v_add_u32_e32 v26, s1, v42
	v_ashrrev_i32_e32 v27, 31, v26
	v_lshlrev_b64 v[26:27], 11, v[26:27]
	v_add_u32_e32 v28, s1, v45
	v_ashrrev_i32_e32 v29, 31, v28
	v_lshlrev_b64 v[62:63], 11, v[28:29]
	s_waitcnt lgkmcnt(0)
	s_barrier
	v_lshl_add_u64 v[28:29], v[58:59], 0, v[22:23]
	v_lshl_add_u64 v[28:29], v[28:29], 0, v[162:163]
	global_load_dwordx4 v[168:171], v[28:29], off
	v_lshl_add_u64 v[30:31], v[60:61], 0, v[22:23]
	global_load_dwordx4 v[172:175], v[30:31], off
	v_lshl_add_u64 v[28:29], v[58:59], 0, v[24:25]
	v_lshl_add_u64 v[28:29], v[28:29], 0, v[162:163]
	global_load_dwordx4 v[176:179], v[28:29], off
	v_lshl_add_u64 v[30:31], v[60:61], 0, v[24:25]
	global_load_dwordx4 v[180:183], v[30:31], off
	v_lshl_add_u64 v[28:29], v[58:59], 0, v[26:27]
	v_lshl_add_u64 v[28:29], v[28:29], 0, v[162:163]
	global_load_dwordx4 v[184:187], v[28:29], off
	v_lshl_add_u64 v[30:31], v[60:61], 0, v[26:27]
	global_load_dwordx4 v[188:191], v[30:31], off
	v_lshl_add_u64 v[28:29], v[58:59], 0, v[62:63]
	v_lshl_add_u64 v[28:29], v[28:29], 0, v[162:163]
	global_load_dwordx4 v[236:239], v[28:29], off
	v_lshl_add_u64 v[30:31], v[60:61], 0, v[62:63]
	global_load_dwordx4 v[240:243], v[30:31], off
	s_lshl_b32 s12, s0, 1
	s_cmp_gt_i32 s11, 3
	s_cselect_b32 s0, 0x87, 3
	s_sub_i32 s13, s0, s11
	s_mov_b32 s14, 0
	s_mov_b64 s[6:7], -1
	s_mov_b64 s[0:1], 0
	s_waitcnt vmcnt(6)
	v_add_u32_e32 v17, v2, v37
	ds_write_b128 v17, v[172:175] offset:20480
	v_add_u32_e32 v165, v38, v164
	ds_write_b16 v165, v168 offset:40960
	ds_write_b16_d16_hi v165, v168 offset:41120
	ds_write_b16 v165, v169 offset:41280
	ds_write_b16_d16_hi v165, v169 offset:41440
	ds_write_b16 v165, v170 offset:41600
	ds_write_b16_d16_hi v165, v170 offset:41760
	ds_write_b16 v165, v171 offset:41920
	ds_write_b16_d16_hi v165, v171 offset:42080
	s_waitcnt vmcnt(4)
	v_add_u32_e32 v17, v2, v40
	ds_write_b128 v17, v[180:183] offset:20480
	v_add_u32_e32 v165, v41, v164
	ds_write_b16 v165, v176 offset:40960
	ds_write_b16_d16_hi v165, v176 offset:41120
	ds_write_b16 v165, v177 offset:41280
	ds_write_b16_d16_hi v165, v177 offset:41440
	ds_write_b16 v165, v178 offset:41600
	ds_write_b16_d16_hi v165, v178 offset:41760
	ds_write_b16 v165, v179 offset:41920
	ds_write_b16_d16_hi v165, v179 offset:42080
	s_waitcnt vmcnt(2)
	v_add_u32_e32 v17, v2, v43
	ds_write_b128 v17, v[188:191] offset:20480
	v_add_u32_e32 v165, v44, v164
	ds_write_b16 v165, v184 offset:40960
	ds_write_b16_d16_hi v165, v184 offset:41120
	ds_write_b16 v165, v185 offset:41280
	ds_write_b16_d16_hi v165, v185 offset:41440
	ds_write_b16 v165, v186 offset:41600
	ds_write_b16_d16_hi v165, v186 offset:41760
	ds_write_b16 v165, v187 offset:41920
	ds_write_b16_d16_hi v165, v187 offset:42080
	s_waitcnt vmcnt(0)
	v_add_u32_e32 v17, v2, v46
	ds_write_b128 v17, v[240:243] offset:20480
	v_add_u32_e32 v165, v47, v164
	ds_write_b16 v165, v236 offset:40960
	ds_write_b16_d16_hi v165, v236 offset:41120
	ds_write_b16 v165, v237 offset:41280
	ds_write_b16_d16_hi v165, v237 offset:41440
	ds_write_b16 v165, v238 offset:41600
	ds_write_b16_d16_hi v165, v238 offset:41760
	ds_write_b16 v165, v239 offset:41920
	ds_write_b16_d16_hi v165, v239 offset:42080
	v_lshl_add_u64 v[54:55], v[12:13], 0, s[52:53]
	v_lshl_add_u64 v[28:29], v[54:55], 0, v[22:23]
	global_load_dwordx4 v[168:171], v[28:29], off
	v_lshl_add_u64 v[28:29], v[54:55], 0, v[24:25]
	global_load_dwordx4 v[172:175], v[28:29], off
	v_lshl_add_u64 v[28:29], v[54:55], 0, v[26:27]
	global_load_dwordx4 v[176:179], v[28:29], off
	v_lshl_add_u64 v[28:29], v[54:55], 0, v[62:63]
	global_load_dwordx4 v[180:183], v[28:29], off
	s_branch .LBB0_307

; DEV void phase_hg_c1(const Params& p, char* smem) {
;     ...
;       if (dir == 1) {
;         __syncthreads();
; #pragma unroll
;         for (int i = 0; i < 4; i++) {
;           int id = tid + i * 256; int s = id >> 4, cc = id & 15;
;           *(uint4*)(RA + s * 144 + cc * 8) = *(const uint4*)(LBp + (size_t)(r0 + s) * 1024 + h * 128 + cc * 8);
;         }
.LBB0_307:
	s_andn2_b64 vcc, exec, s[0:1]
	s_cbranch_vccnz .LBB0_309
	s_waitcnt lgkmcnt(0)
	s_barrier
	s_waitcnt vmcnt(0)
	ds_write_b128 v48, v[168:171]
	ds_write_b128 v49, v[172:175]
	ds_write_b128 v50, v[176:179]
	ds_write_b128 v51, v[180:183]
